# v61 + wave halves stay staggered across GEMM tile boundaries (catch-up barrier only on the last tile, re-stagger barrier dropped): one half's epilogue overlaps the other half's MFMA segment
# speedup vs baseline: 1.0285x; 1.0009x over previous
; __device__ __forceinline__ unsigned cvt_pk_bf16(float lo, float hi) { unsigned r; asm volatile("v_cvt_pk_bf16_f32 %0, %1, %2" : "=v"(r) : "v"(lo), "v"(hi)); return r; }
; #define PG8_BAR __builtin_amdgcn_s_barrier()
; #define PG8_OPQ(p) asm volatile("" : "+v"(p))
; template <class Epi, class Sched>
; __device__ __forceinline__ void gemm_phase(LAS unsigned char* lds, const Gemm g, const Sched& S, const Epi& E) {
;     ...
;         if (wr == 0) PG8_BAR;
;         E(acc, cur, wr, wc, fr, fq); S.done(cur);
;         if (!has_next) break;
; #pragma unroll
;         for (int a = 0; a < 2; ++a)
; #pragma unroll
;             for (int b = 0; b < 2; ++b)
; #pragma unroll
;                 for (int m = 0; m < 4; ++m)
; #pragma unroll
;                     for (int n = 0; n < 2; ++n) acc[a][b][m][n] = (f32x4){0.f, 0.f, 0.f, 0.f};
;         cur = nxt; cA = nA; cB = nB; ++ui;
;         if (wr == 1) PG8_BAR;
;     __device__ __forceinline__ void operator()(const f32x4 (&acc)[2][2][4][2], const Unit& u, int wr, int wc, int fr, int fq) const {
;         char* p = (char*)(O + (size_t)(wr * 64 + fr) * ldc + u.pn * BM + wc * 32 + 8 * fq);
;         const size_t step = (size_t)16 * ldc * 2;
; #pragma unroll
;         for (int ai = 0; ai < 2; ++ai) {
; #pragma unroll
;             for (int m = 0; m < 4; ++m) {
;                 PG8_OPQ(p);
; #pragma unroll
;                 for (int bj = 0; bj < 2; ++bj) { f32x4 v0 = acc[ai][bj][m][0], v1 = acc[ai][bj][m][1];
;                     if (ACT == 1) {
; #pragma unroll
;                         for (int j = 0; j < 4; ++j) { const float a0 = fmaxf(v0[j], 0.f), a1 = fmaxf(v1[j], 0.f); v0[j] = a0 * a0; v1[j] = a1 * a1; } }
;                     u32x4 w; w.x = cvt_pk_bf16(v0[0], v0[1]); w.y = cvt_pk_bf16(v0[2], v0[3]); w.z = cvt_pk_bf16(v1[0], v1[1]); w.w = cvt_pk_bf16(v1[2], v1[3]);
;                     *(u32x4*)(p + bj * HALF * 2) = w; }
;                 p += step;
;             }
;             p += 4 * step;
;         }
;     }
.LBB0_132:
	s_cmp_lg_u32 s8, 8
	s_cbranch_scc1 .LBB0_134
	s_and_b64 vcc, exec, s[42:43]
	s_cbranch_vccz .LBB0_134
	s_barrier
.LBB0_134:
	s_lshl_b32 s36, s8, 8
	v_lshl_add_u64 v[144:145], s[36:37], 1, v[136:137]
	v_cvt_pk_bf16_f32 v122, v122, v123
	v_cvt_pk_bf16_f32 v123, v124, v125
	v_cvt_pk_bf16_f32 v124, v126, v127
	v_cvt_pk_bf16_f32 v125, v128, v129
	global_store_dwordx4 v[144:145], v[122:125], off
	v_cvt_pk_bf16_f32 v118, v118, v119
	v_cvt_pk_bf16_f32 v119, v120, v121
	v_cvt_pk_bf16_f32 v120, v114, v115
	v_lshl_add_u64 v[114:115], v[144:145], 0, s[12:13]
	v_cvt_pk_bf16_f32 v121, v116, v117
	global_store_dwordx4 v[144:145], v[118:121], off offset:256
	v_cvt_pk_bf16_f32 v110, v110, v111
	v_cvt_pk_bf16_f32 v111, v112, v113
	v_cvt_pk_bf16_f32 v112, v106, v107
	v_cvt_pk_bf16_f32 v113, v108, v109
	global_store_dwordx4 v[114:115], v[110:113], off
	v_cvt_pk_bf16_f32 v102, v102, v103
	v_cvt_pk_bf16_f32 v103, v104, v105
	v_cvt_pk_bf16_f32 v104, v98, v99
	v_lshl_add_u64 v[98:99], v[114:115], 0, s[12:13]
	v_cvt_pk_bf16_f32 v105, v100, v101
	global_store_dwordx4 v[114:115], v[102:105], off offset:256
	v_cvt_pk_bf16_f32 v94, v94, v95
	v_cvt_pk_bf16_f32 v95, v96, v97
	v_cvt_pk_bf16_f32 v96, v90, v91
	v_cvt_pk_bf16_f32 v97, v92, v93
	global_store_dwordx4 v[98:99], v[94:97], off
	v_cvt_pk_bf16_f32 v86, v86, v87
	v_cvt_pk_bf16_f32 v87, v88, v89
	v_cvt_pk_bf16_f32 v88, v82, v83
	v_lshl_add_u64 v[82:83], v[98:99], 0, s[12:13]
	s_mov_b64 s[46:47], 0x64000
	v_cvt_pk_bf16_f32 v89, v84, v85
	global_store_dwordx4 v[98:99], v[86:89], off offset:256
	v_cvt_pk_bf16_f32 v78, v78, v79
	v_cvt_pk_bf16_f32 v79, v80, v81
	v_cvt_pk_bf16_f32 v80, v74, v75
	v_cvt_pk_bf16_f32 v81, v76, v77
	global_store_dwordx4 v[82:83], v[78:81], off
	v_cvt_pk_bf16_f32 v70, v70, v71
	v_cvt_pk_bf16_f32 v71, v72, v73
	v_cvt_pk_bf16_f32 v72, v66, v67
	v_lshl_add_u64 v[66:67], v[82:83], 0, s[46:47]
	v_cvt_pk_bf16_f32 v73, v68, v69
	global_store_dwordx4 v[82:83], v[70:73], off offset:256
	v_cvt_pk_bf16_f32 v62, v62, v63
	v_cvt_pk_bf16_f32 v63, v64, v65
	v_cvt_pk_bf16_f32 v64, v58, v59
	v_cvt_pk_bf16_f32 v65, v60, v61
	global_store_dwordx4 v[66:67], v[62:65], off
	v_cvt_pk_bf16_f32 v54, v54, v55
	v_cvt_pk_bf16_f32 v55, v56, v57
	v_cvt_pk_bf16_f32 v56, v50, v51
	v_lshl_add_u64 v[50:51], v[66:67], 0, s[12:13]
	v_cvt_pk_bf16_f32 v57, v52, v53
	global_store_dwordx4 v[66:67], v[54:57], off offset:256
	v_cvt_pk_bf16_f32 v46, v46, v47
	v_cvt_pk_bf16_f32 v47, v48, v49
	v_cvt_pk_bf16_f32 v48, v42, v43
	v_cvt_pk_bf16_f32 v49, v44, v45
	global_store_dwordx4 v[50:51], v[46:49], off
	v_cvt_pk_bf16_f32 v38, v38, v39
	v_cvt_pk_bf16_f32 v39, v40, v41
	v_cvt_pk_bf16_f32 v40, v34, v35
	v_lshl_add_u64 v[34:35], v[50:51], 0, s[12:13]
	v_cvt_pk_bf16_f32 v41, v36, v37
	global_store_dwordx4 v[50:51], v[38:41], off offset:256
	v_cvt_pk_bf16_f32 v30, v30, v31
	v_cvt_pk_bf16_f32 v31, v32, v33
	v_cvt_pk_bf16_f32 v32, v26, v27
	v_cvt_pk_bf16_f32 v33, v28, v29
	global_store_dwordx4 v[34:35], v[30:33], off
	v_cvt_pk_bf16_f32 v22, v22, v23
	v_cvt_pk_bf16_f32 v23, v24, v25
	v_cvt_pk_bf16_f32 v24, v18, v19
	v_lshl_add_u64 v[18:19], v[34:35], 0, s[12:13]
	s_cmp_eq_u32 s8, 8
	s_mov_b64 s[8:9], -1
	v_cvt_pk_bf16_f32 v25, v20, v21
	global_store_dwordx4 v[34:35], v[22:25], off offset:256
	v_cvt_pk_bf16_f32 v14, v14, v15
	v_cvt_pk_bf16_f32 v15, v16, v17
	v_cvt_pk_bf16_f32 v16, v10, v11
	v_cvt_pk_bf16_f32 v17, v12, v13
	global_store_dwordx4 v[18:19], v[14:17], off
	v_cvt_pk_bf16_f32 v6, v6, v7
	v_cvt_pk_bf16_f32 v7, v8, v9
	v_cvt_pk_bf16_f32 v8, v2, v3
	v_cvt_pk_bf16_f32 v9, v4, v5
	global_store_dwordx4 v[18:19], v[6:9], off offset:256
	s_cbranch_scc1 .LBB0_126
	s_andn2_b64 vcc, exec, s[26:27]
	s_cbranch_vccnz .LBB0_125
	s_branch .LBB0_125

; __device__ __forceinline__ float bflo_(unsigned w) { return __uint_as_float(w << 16); }
; __device__ __forceinline__ float bfhi_(unsigned w) { return __uint_as_float(w & 0xffff0000u); }
; __device__ __forceinline__ unsigned cvt_pk_bf16(float lo, float hi) { unsigned r; asm volatile("v_cvt_pk_bf16_f32 %0, %1, %2" : "=v"(r) : "v"(lo), "v"(hi)); return r; }
; #define PG8_BAR __builtin_amdgcn_s_barrier()
; #define PG8_OPQ(p) asm volatile("" : "+v"(p))
; template <class Epi, class Sched>
; __device__ __forceinline__ void gemm_phase(LAS unsigned char* lds, const Gemm g, const Sched& S, const Epi& E) {
;     ...
;         if (wr == 0) PG8_BAR;
;         E(acc, cur, wr, wc, fr, fq); S.done(cur);
;     __device__ __forceinline__ void operator()(const f32x4 (&acc)[2][2][4][2], const Unit& u, int wr, int wc, int fr, int fq) const {
;         char* p = (char*)(HB + (size_t)(wr * 64 + fr) * ldc + u.pn * BM + wc * 32 + 8 * fq);
;         const size_t step = (size_t)16 * ldc * 2;
; #pragma unroll
;         for (int ai = 0; ai < 2; ++ai) {
;             PG8_OPQ(p);
;             u32x4 h[4][2];
; #pragma unroll
;             for (int m = 0; m < 4; ++m)
; #pragma unroll
;                 for (int bj = 0; bj < 2; ++bj) h[m][bj] = *(const u32x4*)(p + m * step + bj * HALF * 2);
; #pragma unroll
;             for (int m = 0; m < 4; ++m)
; #pragma unroll
;                 for (int bj = 0; bj < 2; ++bj) { const f32x4 v0 = acc[ai][bj][m][0], v1 = acc[ai][bj][m][1]; const u32x4 hh = h[m][bj];
;                     u32x4 w;
;                     w.x = cvt_pk_bf16(bflo_(hh.x) * alpha + v0[0], bfhi_(hh.x) * alpha + v0[1]); w.y = cvt_pk_bf16(bflo_(hh.y) * alpha + v0[2], bfhi_(hh.y) * alpha + v0[3]);
;                     w.z = cvt_pk_bf16(bflo_(hh.z) * alpha + v1[0], bfhi_(hh.z) * alpha + v1[1]); w.w = cvt_pk_bf16(bflo_(hh.w) * alpha + v1[2], bfhi_(hh.w) * alpha + v1[3]);
;                     *(u32x4*)(p + m * step + bj * HALF * 2) = w; }
;             p += 8 * step;
;         }
.LBB0_419:
	s_cmp_lg_u32 s8, 3
	s_cbranch_scc1 .LBB0_421
	s_and_b64 vcc, exec, s[44:45]
	s_cbranch_vccz .LBB0_421
	s_barrier
.LBB0_421:
	s_lshl_b32 s36, s8, 8
	v_lshl_add_u64 v[154:155], s[36:37], 1, v[148:149]
	global_load_dwordx4 v[162:165], v[154:155], off
	global_load_dwordx4 v[166:169], v[154:155], off offset:256
	v_add_co_u32_e32 v182, vcc, 0x8000, v154
	s_cmp_eq_u32 s8, 3
	s_nop 0
	v_addc_co_u32_e32 v183, vcc, 0, v155, vcc
	global_load_dwordx4 v[170:173], v[182:183], off
	global_load_dwordx4 v[174:177], v[182:183], off offset:256
	v_add_co_u32_e32 v158, vcc, 0x10000, v154
	s_mov_b64 s[8:9], -1
	s_nop 0
	v_addc_co_u32_e32 v159, vcc, 0, v155, vcc
	global_load_dwordx4 v[178:181], v[158:159], off
	global_load_dwordx4 v[138:141], v[158:159], off offset:256
	v_add_co_u32_e32 v156, vcc, 0x18000, v154
	s_waitcnt vmcnt(0) lgkmcnt(0)
	v_lshlrev_b32_e32 v184, 16, v162
	v_addc_co_u32_e32 v157, vcc, 0, v155, vcc
	global_load_dwordx4 v[134:137], v[156:157], off
	global_load_dwordx4 v[130:133], v[156:157], off offset:256
	v_and_b32_e32 v162, 0xffff0000, v162
	v_lshlrev_b32_e32 v185, 16, v163
	v_and_b32_e32 v163, 0xffff0000, v163
	v_lshlrev_b32_e32 v186, 16, v164
	v_and_b32_e32 v164, 0xffff0000, v164
	v_lshlrev_b32_e32 v187, 16, v165
	v_and_b32_e32 v165, 0xffff0000, v165
	v_fmac_f32_e32 v122, 0x3fb504f3, v184
	v_fmac_f32_e32 v123, 0x3fb504f3, v162
	v_fmac_f32_e32 v124, 0x3fb504f3, v185
	v_fmac_f32_e32 v125, 0x3fb504f3, v163
	v_fmac_f32_e32 v126, 0x3fb504f3, v186
	v_fmac_f32_e32 v127, 0x3fb504f3, v164
	v_fmac_f32_e32 v128, 0x3fb504f3, v187
	v_lshlrev_b32_e32 v188, 16, v166
	v_and_b32_e32 v166, 0xffff0000, v166
	v_lshlrev_b32_e32 v190, 16, v167
	v_and_b32_e32 v167, 0xffff0000, v167
	v_fmac_f32_e32 v129, 0x3fb504f3, v165
	v_cvt_pk_bf16_f32 v122, v122, v123
	v_cvt_pk_bf16_f32 v123, v124, v125
	v_cvt_pk_bf16_f32 v124, v126, v127
	v_cvt_pk_bf16_f32 v125, v128, v129
	v_lshlrev_b32_e32 v126, 16, v170
	v_and_b32_e32 v127, 0xffff0000, v170
	v_lshlrev_b32_e32 v128, 16, v171
	v_lshlrev_b32_e32 v162, 16, v172
	v_lshlrev_b32_e32 v192, 16, v168
	v_and_b32_e32 v168, 0xffff0000, v168
	v_lshlrev_b32_e32 v193, 16, v169
	v_and_b32_e32 v169, 0xffff0000, v169
	v_fmac_f32_e32 v118, 0x3fb504f3, v188
	v_fmac_f32_e32 v119, 0x3fb504f3, v166
	v_fmac_f32_e32 v120, 0x3fb504f3, v190
	v_fmac_f32_e32 v121, 0x3fb504f3, v167
	v_and_b32_e32 v129, 0xffff0000, v171
	v_and_b32_e32 v163, 0xffff0000, v172
	v_fmac_f32_e32 v110, 0x3fb504f3, v126
	v_fmac_f32_e32 v111, 0x3fb504f3, v127
	v_fmac_f32_e32 v112, 0x3fb504f3, v128
	v_fmac_f32_e32 v106, 0x3fb504f3, v162
	v_fmac_f32_e32 v114, 0x3fb504f3, v192
	v_fmac_f32_e32 v115, 0x3fb504f3, v168
	v_fmac_f32_e32 v116, 0x3fb504f3, v193
	v_fmac_f32_e32 v117, 0x3fb504f3, v169
	global_store_dwordx4 v[154:155], v[122:125], off
	v_cvt_pk_bf16_f32 v118, v118, v119
	v_cvt_pk_bf16_f32 v119, v120, v121
	v_cvt_pk_bf16_f32 v120, v114, v115
	v_cvt_pk_bf16_f32 v121, v116, v117
	v_fmac_f32_e32 v113, 0x3fb504f3, v129
	v_fmac_f32_e32 v107, 0x3fb504f3, v163
	global_store_dwordx4 v[154:155], v[118:121], off offset:256
	v_cvt_pk_bf16_f32 v110, v110, v111
	v_cvt_pk_bf16_f32 v111, v112, v113
	v_cvt_pk_bf16_f32 v112, v106, v107
	v_lshlrev_b32_e32 v106, 16, v174
	v_fmac_f32_e32 v102, 0x3fb504f3, v106
	v_and_b32_e32 v106, 0xffff0000, v174
	v_lshlrev_b32_e32 v164, 16, v173
	v_and_b32_e32 v165, 0xffff0000, v173
	v_fmac_f32_e32 v103, 0x3fb504f3, v106
	v_fmac_f32_e32 v108, 0x3fb504f3, v164
	v_fmac_f32_e32 v109, 0x3fb504f3, v165
	v_cvt_pk_bf16_f32 v113, v108, v109
	global_store_dwordx4 v[182:183], v[110:113], off
	v_cvt_pk_bf16_f32 v102, v102, v103
	v_lshlrev_b32_e32 v103, 16, v175
	v_fmac_f32_e32 v104, 0x3fb504f3, v103
	v_and_b32_e32 v103, 0xffff0000, v175
	v_fmac_f32_e32 v105, 0x3fb504f3, v103
	v_cvt_pk_bf16_f32 v103, v104, v105
	v_lshlrev_b32_e32 v104, 16, v176
	v_fmac_f32_e32 v98, 0x3fb504f3, v104
	v_and_b32_e32 v104, 0xffff0000, v176
	v_fmac_f32_e32 v99, 0x3fb504f3, v104
	v_cvt_pk_bf16_f32 v104, v98, v99
	v_lshlrev_b32_e32 v98, 16, v177
	v_fmac_f32_e32 v100, 0x3fb504f3, v98
	v_and_b32_e32 v98, 0xffff0000, v177
	v_fmac_f32_e32 v101, 0x3fb504f3, v98
	v_lshlrev_b32_e32 v98, 16, v178
	v_fmac_f32_e32 v94, 0x3fb504f3, v98
	v_and_b32_e32 v98, 0xffff0000, v178
	v_fmac_f32_e32 v95, 0x3fb504f3, v98
	v_cvt_pk_bf16_f32 v105, v100, v101
	global_store_dwordx4 v[182:183], v[102:105], off offset:256
	v_cvt_pk_bf16_f32 v94, v94, v95
	v_lshlrev_b32_e32 v95, 16, v179
	v_fmac_f32_e32 v96, 0x3fb504f3, v95
	v_and_b32_e32 v95, 0xffff0000, v179
	v_fmac_f32_e32 v97, 0x3fb504f3, v95
	v_cvt_pk_bf16_f32 v95, v96, v97
	v_lshlrev_b32_e32 v96, 16, v180
	v_fmac_f32_e32 v90, 0x3fb504f3, v96
	v_and_b32_e32 v96, 0xffff0000, v180
	v_fmac_f32_e32 v91, 0x3fb504f3, v96
	v_cvt_pk_bf16_f32 v96, v90, v91
	v_lshlrev_b32_e32 v90, 16, v181
	v_fmac_f32_e32 v92, 0x3fb504f3, v90
	v_and_b32_e32 v90, 0xffff0000, v181
	v_fmac_f32_e32 v93, 0x3fb504f3, v90
	v_lshlrev_b32_e32 v90, 16, v138
	v_fmac_f32_e32 v86, 0x3fb504f3, v90
	v_and_b32_e32 v90, 0xffff0000, v138
	v_fmac_f32_e32 v87, 0x3fb504f3, v90
	v_cvt_pk_bf16_f32 v97, v92, v93
	global_store_dwordx4 v[158:159], v[94:97], off
	v_cvt_pk_bf16_f32 v86, v86, v87
	v_lshlrev_b32_e32 v87, 16, v139
	v_fmac_f32_e32 v88, 0x3fb504f3, v87
	v_and_b32_e32 v87, 0xffff0000, v139
	v_fmac_f32_e32 v89, 0x3fb504f3, v87
	v_cvt_pk_bf16_f32 v87, v88, v89
	v_lshlrev_b32_e32 v88, 16, v140
	v_fmac_f32_e32 v82, 0x3fb504f3, v88
	v_and_b32_e32 v88, 0xffff0000, v140
	v_fmac_f32_e32 v83, 0x3fb504f3, v88
	v_cvt_pk_bf16_f32 v88, v82, v83
	v_lshlrev_b32_e32 v82, 16, v141
	v_fmac_f32_e32 v84, 0x3fb504f3, v82
	v_and_b32_e32 v82, 0xffff0000, v141
	v_fmac_f32_e32 v85, 0x3fb504f3, v82
	s_waitcnt vmcnt(5) lgkmcnt(0)
; __device__ __forceinline__ float bflo_(unsigned w) { return __uint_as_float(w << 16); }
; __device__ __forceinline__ float bfhi_(unsigned w) { return __uint_as_float(w & 0xffff0000u); }
; __device__ __forceinline__ unsigned cvt_pk_bf16(float lo, float hi) { unsigned r; asm volatile("v_cvt_pk_bf16_f32 %0, %1, %2" : "=v"(r) : "v"(lo), "v"(hi)); return r; }
; #define PG8_OPQ(p) asm volatile("" : "+v"(p))
;     __device__ __forceinline__ void operator()(const f32x4 (&acc)[2][2][4][2], const Unit& u, int wr, int wc, int fr, int fq) const {
;     ...
;         for (int ai = 0; ai < 2; ++ai) {
;             PG8_OPQ(p);
;             u32x4 h[4][2];
; #pragma unroll
;             for (int m = 0; m < 4; ++m)
; #pragma unroll
;                 for (int bj = 0; bj < 2; ++bj) h[m][bj] = *(const u32x4*)(p + m * step + bj * HALF * 2);
; #pragma unroll
;             for (int m = 0; m < 4; ++m)
; #pragma unroll
;                 for (int bj = 0; bj < 2; ++bj) { const f32x4 v0 = acc[ai][bj][m][0], v1 = acc[ai][bj][m][1]; const u32x4 hh = h[m][bj];
;                     u32x4 w;
;                     w.x = cvt_pk_bf16(bflo_(hh.x) * alpha + v0[0], bfhi_(hh.x) * alpha + v0[1]); w.y = cvt_pk_bf16(bflo_(hh.y) * alpha + v0[2], bfhi_(hh.y) * alpha + v0[3]);
;                     w.z = cvt_pk_bf16(bflo_(hh.z) * alpha + v1[0], bfhi_(hh.z) * alpha + v1[1]); w.w = cvt_pk_bf16(bflo_(hh.w) * alpha + v1[2], bfhi_(hh.w) * alpha + v1[3]);
;                     *(u32x4*)(p + m * step + bj * HALF * 2) = w; }
;             p += 8 * step;
;         }
	v_lshlrev_b32_e32 v82, 16, v134
	v_fmac_f32_e32 v78, 0x3fb504f3, v82
	v_and_b32_e32 v82, 0xffff0000, v134
	v_fmac_f32_e32 v79, 0x3fb504f3, v82
	v_cvt_pk_bf16_f32 v89, v84, v85
	global_store_dwordx4 v[158:159], v[86:89], off offset:256
	v_cvt_pk_bf16_f32 v78, v78, v79
	v_lshlrev_b32_e32 v79, 16, v135
	v_fmac_f32_e32 v80, 0x3fb504f3, v79
	v_and_b32_e32 v79, 0xffff0000, v135
	v_fmac_f32_e32 v81, 0x3fb504f3, v79
	v_cvt_pk_bf16_f32 v79, v80, v81
	v_lshlrev_b32_e32 v80, 16, v136
	v_fmac_f32_e32 v74, 0x3fb504f3, v80
	v_and_b32_e32 v80, 0xffff0000, v136
	v_fmac_f32_e32 v75, 0x3fb504f3, v80
	v_cvt_pk_bf16_f32 v80, v74, v75
	v_lshlrev_b32_e32 v74, 16, v137
	v_fmac_f32_e32 v76, 0x3fb504f3, v74
	v_and_b32_e32 v74, 0xffff0000, v137
	v_fmac_f32_e32 v77, 0x3fb504f3, v74
	v_lshlrev_b32_e32 v74, 16, v130
	v_fmac_f32_e32 v70, 0x3fb504f3, v74
	v_and_b32_e32 v74, 0xffff0000, v130
	v_fmac_f32_e32 v71, 0x3fb504f3, v74
	v_cvt_pk_bf16_f32 v81, v76, v77
	global_store_dwordx4 v[156:157], v[78:81], off
	v_cvt_pk_bf16_f32 v70, v70, v71
	v_lshlrev_b32_e32 v71, 16, v131
	v_fmac_f32_e32 v72, 0x3fb504f3, v71
	v_and_b32_e32 v71, 0xffff0000, v131
	v_fmac_f32_e32 v73, 0x3fb504f3, v71
	v_cvt_pk_bf16_f32 v71, v72, v73
	v_lshlrev_b32_e32 v72, 16, v132
	v_fmac_f32_e32 v66, 0x3fb504f3, v72
	v_and_b32_e32 v72, 0xffff0000, v132
	v_fmac_f32_e32 v67, 0x3fb504f3, v72
	v_cvt_pk_bf16_f32 v72, v66, v67
	v_lshlrev_b32_e32 v66, 16, v133
	v_fmac_f32_e32 v68, 0x3fb504f3, v66
	v_and_b32_e32 v66, 0xffff0000, v133
	v_lshl_add_u64 v[100:101], v[154:155], 0, s[24:25]
	v_fmac_f32_e32 v69, 0x3fb504f3, v66
	v_cvt_pk_bf16_f32 v73, v68, v69
	global_store_dwordx4 v[156:157], v[70:73], off offset:256
	global_load_dwordx4 v[72:75], v[100:101], off
	global_load_dwordx4 v[76:79], v[100:101], off offset:256
	v_add_co_u32_e32 v102, vcc, s87, v100
	s_waitcnt vmcnt(0) lgkmcnt(0)
	v_lshlrev_b32_e32 v106, 16, v72
	v_addc_co_u32_e32 v103, vcc, 0, v101, vcc
	global_load_dwordx4 v[80:83], v[102:103], off
	global_load_dwordx4 v[84:87], v[102:103], off offset:256
	v_add_co_u32_e32 v104, vcc, s91, v100
	v_and_b32_e32 v72, 0xffff0000, v72
	s_nop 0
	v_addc_co_u32_e32 v105, vcc, 0, v101, vcc
	global_load_dwordx4 v[88:91], v[104:105], off
	global_load_dwordx4 v[92:95], v[104:105], off offset:256
	v_add_co_u32_e32 v70, vcc, s86, v100
	v_fmac_f32_e32 v62, 0x3fb504f3, v106
	s_nop 0
	v_addc_co_u32_e32 v71, vcc, 0, v101, vcc
	global_load_dwordx4 v[96:99], v[70:71], off
	global_load_dwordx4 v[66:69], v[70:71], off offset:256
	v_fmac_f32_e32 v63, 0x3fb504f3, v72
	v_cvt_pk_bf16_f32 v62, v62, v63
	v_lshlrev_b32_e32 v63, 16, v73
	v_fmac_f32_e32 v64, 0x3fb504f3, v63
	v_and_b32_e32 v63, 0xffff0000, v73
	v_fmac_f32_e32 v65, 0x3fb504f3, v63
	v_cvt_pk_bf16_f32 v63, v64, v65
	v_lshlrev_b32_e32 v64, 16, v74
	v_fmac_f32_e32 v58, 0x3fb504f3, v64
	v_and_b32_e32 v64, 0xffff0000, v74
	v_fmac_f32_e32 v59, 0x3fb504f3, v64
	v_cvt_pk_bf16_f32 v64, v58, v59
	v_lshlrev_b32_e32 v58, 16, v75
	v_fmac_f32_e32 v60, 0x3fb504f3, v58
	v_and_b32_e32 v58, 0xffff0000, v75
	v_fmac_f32_e32 v61, 0x3fb504f3, v58
	v_lshlrev_b32_e32 v58, 16, v76
	v_fmac_f32_e32 v54, 0x3fb504f3, v58
	v_and_b32_e32 v58, 0xffff0000, v76
	v_fmac_f32_e32 v55, 0x3fb504f3, v58
	v_cvt_pk_bf16_f32 v65, v60, v61
	global_store_dwordx4 v[100:101], v[62:65], off
	v_cvt_pk_bf16_f32 v54, v54, v55
	v_lshlrev_b32_e32 v55, 16, v77
	v_fmac_f32_e32 v56, 0x3fb504f3, v55
	v_and_b32_e32 v55, 0xffff0000, v77
	v_fmac_f32_e32 v57, 0x3fb504f3, v55
	v_cvt_pk_bf16_f32 v55, v56, v57
	v_lshlrev_b32_e32 v56, 16, v78
	v_fmac_f32_e32 v50, 0x3fb504f3, v56
	v_and_b32_e32 v56, 0xffff0000, v78
	v_fmac_f32_e32 v51, 0x3fb504f3, v56
	v_cvt_pk_bf16_f32 v56, v50, v51
	v_lshlrev_b32_e32 v50, 16, v79
	v_fmac_f32_e32 v52, 0x3fb504f3, v50
	v_and_b32_e32 v50, 0xffff0000, v79
	v_fmac_f32_e32 v53, 0x3fb504f3, v50
	v_cvt_pk_bf16_f32 v57, v52, v53
	global_store_dwordx4 v[100:101], v[54:57], off offset:256
	s_waitcnt vmcnt(2) lgkmcnt(0)
; __device__ __forceinline__ float bflo_(unsigned w) { return __uint_as_float(w << 16); }
; __device__ __forceinline__ float bfhi_(unsigned w) { return __uint_as_float(w & 0xffff0000u); }
; __device__ __forceinline__ unsigned cvt_pk_bf16(float lo, float hi) { unsigned r; asm volatile("v_cvt_pk_bf16_f32 %0, %1, %2" : "=v"(r) : "v"(lo), "v"(hi)); return r; }
; #define PG8_BAR __builtin_amdgcn_s_barrier()
; #define PG8_OPQ(p) asm volatile("" : "+v"(p))
; template <class Epi, class Sched>
; __device__ __forceinline__ void gemm_phase(LAS unsigned char* lds, const Gemm g, const Sched& S, const Epi& E) {
;     ...
;         if (wr == 0) PG8_BAR;
;         E(acc, cur, wr, wc, fr, fq); S.done(cur);
;         if (!has_next) break;
; #pragma unroll
;         for (int a = 0; a < 2; ++a)
; #pragma unroll
;             for (int b = 0; b < 2; ++b)
; #pragma unroll
;                 for (int m = 0; m < 4; ++m)
; #pragma unroll
;                     for (int n = 0; n < 2; ++n) acc[a][b][m][n] = (f32x4){0.f, 0.f, 0.f, 0.f};
;         cur = nxt; cA = nA; cB = nB; ++ui;
;         if (wr == 1) PG8_BAR;
;     __device__ __forceinline__ void operator()(const f32x4 (&acc)[2][2][4][2], const Unit& u, int wr, int wc, int fr, int fq) const {
;     ...
;         for (int ai = 0; ai < 2; ++ai) {
;             PG8_OPQ(p);
;             u32x4 h[4][2];
; #pragma unroll
;             for (int m = 0; m < 4; ++m)
; #pragma unroll
;                 for (int bj = 0; bj < 2; ++bj) h[m][bj] = *(const u32x4*)(p + m * step + bj * HALF * 2);
; #pragma unroll
;             for (int m = 0; m < 4; ++m)
; #pragma unroll
;                 for (int bj = 0; bj < 2; ++bj) { const f32x4 v0 = acc[ai][bj][m][0], v1 = acc[ai][bj][m][1]; const u32x4 hh = h[m][bj];
;                     u32x4 w;
;                     w.x = cvt_pk_bf16(bflo_(hh.x) * alpha + v0[0], bfhi_(hh.x) * alpha + v0[1]); w.y = cvt_pk_bf16(bflo_(hh.y) * alpha + v0[2], bfhi_(hh.y) * alpha + v0[3]);
;                     w.z = cvt_pk_bf16(bflo_(hh.z) * alpha + v1[0], bfhi_(hh.z) * alpha + v1[1]); w.w = cvt_pk_bf16(bflo_(hh.w) * alpha + v1[2], bfhi_(hh.w) * alpha + v1[3]);
;                     *(u32x4*)(p + m * step + bj * HALF * 2) = w; }
;             p += 8 * step;
;         }
	v_lshlrev_b32_e32 v50, 16, v80
	v_fmac_f32_e32 v46, 0x3fb504f3, v50
	v_and_b32_e32 v50, 0xffff0000, v80
	v_fmac_f32_e32 v47, 0x3fb504f3, v50
	v_cvt_pk_bf16_f32 v46, v46, v47
	v_lshlrev_b32_e32 v47, 16, v81
	v_fmac_f32_e32 v48, 0x3fb504f3, v47
	v_and_b32_e32 v47, 0xffff0000, v81
	v_fmac_f32_e32 v49, 0x3fb504f3, v47
	v_cvt_pk_bf16_f32 v47, v48, v49
	v_lshlrev_b32_e32 v48, 16, v82
	v_fmac_f32_e32 v42, 0x3fb504f3, v48
	v_and_b32_e32 v48, 0xffff0000, v82
	v_fmac_f32_e32 v43, 0x3fb504f3, v48
	v_cvt_pk_bf16_f32 v48, v42, v43
	v_lshlrev_b32_e32 v42, 16, v83
	v_fmac_f32_e32 v44, 0x3fb504f3, v42
	v_and_b32_e32 v42, 0xffff0000, v83
	v_fmac_f32_e32 v45, 0x3fb504f3, v42
	v_lshlrev_b32_e32 v42, 16, v84
	v_fmac_f32_e32 v38, 0x3fb504f3, v42
	v_and_b32_e32 v42, 0xffff0000, v84
	v_fmac_f32_e32 v39, 0x3fb504f3, v42
	v_cvt_pk_bf16_f32 v49, v44, v45
	global_store_dwordx4 v[102:103], v[46:49], off
	v_cvt_pk_bf16_f32 v38, v38, v39
	v_lshlrev_b32_e32 v39, 16, v85
	v_fmac_f32_e32 v40, 0x3fb504f3, v39
	v_and_b32_e32 v39, 0xffff0000, v85
	v_fmac_f32_e32 v41, 0x3fb504f3, v39
	v_cvt_pk_bf16_f32 v39, v40, v41
	v_lshlrev_b32_e32 v40, 16, v86
	v_fmac_f32_e32 v34, 0x3fb504f3, v40
	v_and_b32_e32 v40, 0xffff0000, v86
	v_fmac_f32_e32 v35, 0x3fb504f3, v40
	v_cvt_pk_bf16_f32 v40, v34, v35
	v_lshlrev_b32_e32 v34, 16, v87
	v_fmac_f32_e32 v36, 0x3fb504f3, v34
	v_and_b32_e32 v34, 0xffff0000, v87
	v_fmac_f32_e32 v37, 0x3fb504f3, v34
	v_lshlrev_b32_e32 v34, 16, v88
	v_fmac_f32_e32 v30, 0x3fb504f3, v34
	v_and_b32_e32 v34, 0xffff0000, v88
	v_fmac_f32_e32 v31, 0x3fb504f3, v34
	v_cvt_pk_bf16_f32 v41, v36, v37
	global_store_dwordx4 v[102:103], v[38:41], off offset:256
	v_cvt_pk_bf16_f32 v30, v30, v31
	v_lshlrev_b32_e32 v31, 16, v89
	v_fmac_f32_e32 v32, 0x3fb504f3, v31
	v_and_b32_e32 v31, 0xffff0000, v89
	v_fmac_f32_e32 v33, 0x3fb504f3, v31
	v_cvt_pk_bf16_f32 v31, v32, v33
	v_lshlrev_b32_e32 v32, 16, v90
	v_fmac_f32_e32 v26, 0x3fb504f3, v32
	v_and_b32_e32 v32, 0xffff0000, v90
	v_fmac_f32_e32 v27, 0x3fb504f3, v32
	v_cvt_pk_bf16_f32 v32, v26, v27
	v_lshlrev_b32_e32 v26, 16, v91
	v_fmac_f32_e32 v28, 0x3fb504f3, v26
	v_and_b32_e32 v26, 0xffff0000, v91
	v_fmac_f32_e32 v29, 0x3fb504f3, v26
	v_lshlrev_b32_e32 v26, 16, v92
	v_fmac_f32_e32 v22, 0x3fb504f3, v26
	v_and_b32_e32 v26, 0xffff0000, v92
	v_fmac_f32_e32 v23, 0x3fb504f3, v26
	v_cvt_pk_bf16_f32 v33, v28, v29
	global_store_dwordx4 v[104:105], v[30:33], off
	v_cvt_pk_bf16_f32 v22, v22, v23
	v_lshlrev_b32_e32 v23, 16, v93
	v_fmac_f32_e32 v24, 0x3fb504f3, v23
	v_and_b32_e32 v23, 0xffff0000, v93
	v_fmac_f32_e32 v25, 0x3fb504f3, v23
	v_cvt_pk_bf16_f32 v23, v24, v25
	v_lshlrev_b32_e32 v24, 16, v94
	v_fmac_f32_e32 v18, 0x3fb504f3, v24
	v_and_b32_e32 v24, 0xffff0000, v94
	v_fmac_f32_e32 v19, 0x3fb504f3, v24
	v_cvt_pk_bf16_f32 v24, v18, v19
	v_lshlrev_b32_e32 v18, 16, v95
	v_fmac_f32_e32 v20, 0x3fb504f3, v18
	v_and_b32_e32 v18, 0xffff0000, v95
	v_fmac_f32_e32 v21, 0x3fb504f3, v18
	v_lshlrev_b32_e32 v18, 16, v96
	v_fmac_f32_e32 v14, 0x3fb504f3, v18
	v_and_b32_e32 v18, 0xffff0000, v96
	v_fmac_f32_e32 v15, 0x3fb504f3, v18
	v_cvt_pk_bf16_f32 v25, v20, v21
	global_store_dwordx4 v[104:105], v[22:25], off offset:256
	v_cvt_pk_bf16_f32 v14, v14, v15
	v_lshlrev_b32_e32 v15, 16, v97
	v_fmac_f32_e32 v16, 0x3fb504f3, v15
	v_and_b32_e32 v15, 0xffff0000, v97
	v_fmac_f32_e32 v17, 0x3fb504f3, v15
	v_cvt_pk_bf16_f32 v15, v16, v17
	v_lshlrev_b32_e32 v16, 16, v98
	v_fmac_f32_e32 v10, 0x3fb504f3, v16
	v_and_b32_e32 v16, 0xffff0000, v98
	v_fmac_f32_e32 v11, 0x3fb504f3, v16
	v_cvt_pk_bf16_f32 v16, v10, v11
	v_lshlrev_b32_e32 v10, 16, v99
	v_fmac_f32_e32 v12, 0x3fb504f3, v10
	v_and_b32_e32 v10, 0xffff0000, v99
	v_fmac_f32_e32 v13, 0x3fb504f3, v10
	v_lshlrev_b32_e32 v10, 16, v66
	v_fmac_f32_e32 v6, 0x3fb504f3, v10
	v_and_b32_e32 v10, 0xffff0000, v66
	v_fmac_f32_e32 v7, 0x3fb504f3, v10
	v_cvt_pk_bf16_f32 v17, v12, v13
	global_store_dwordx4 v[70:71], v[14:17], off
	v_cvt_pk_bf16_f32 v6, v6, v7
	v_lshlrev_b32_e32 v7, 16, v67
	v_fmac_f32_e32 v8, 0x3fb504f3, v7
	v_and_b32_e32 v7, 0xffff0000, v67
	v_fmac_f32_e32 v9, 0x3fb504f3, v7
	v_cvt_pk_bf16_f32 v7, v8, v9
	v_lshlrev_b32_e32 v8, 16, v68
	v_fmac_f32_e32 v2, 0x3fb504f3, v8
	v_and_b32_e32 v8, 0xffff0000, v68
	v_fmac_f32_e32 v3, 0x3fb504f3, v8
	v_cvt_pk_bf16_f32 v8, v2, v3
	v_lshlrev_b32_e32 v2, 16, v69
	v_fmac_f32_e32 v4, 0x3fb504f3, v2
	v_and_b32_e32 v2, 0xffff0000, v69
	v_fmac_f32_e32 v5, 0x3fb504f3, v2
	v_cvt_pk_bf16_f32 v9, v4, v5
	global_store_dwordx4 v[70:71], v[6:9], off offset:256
	s_cbranch_scc1 .LBB0_413
	s_andn2_b64 vcc, exec, s[38:39]
	s_cbranch_vccnz .LBB0_412
	s_branch .LBB0_412

; __device__ __forceinline__ unsigned cvt_pk_bf16(float lo, float hi) { unsigned r; asm volatile("v_cvt_pk_bf16_f32 %0, %1, %2" : "=v"(r) : "v"(lo), "v"(hi)); return r; }
; #define PG8_BAR __builtin_amdgcn_s_barrier()
; #define PG8_OPQ(p) asm volatile("" : "+v"(p))
; template <class Epi, class Sched>
; __device__ __forceinline__ void gemm_phase(LAS unsigned char* lds, const Gemm g, const Sched& S, const Epi& E) {
;     ...
;         if (wr == 0) PG8_BAR;
;         E(acc, cur, wr, wc, fr, fq); S.done(cur);
;     __device__ __forceinline__ void operator()(const f32x4 (&acc)[2][2][4][2], const Unit& u, int wr, int wc, int fr, int fq) const {
;         char* p = (char*)(O + (size_t)(wr * 64 + fr) * ldc + u.pn * BM + wc * 32 + 8 * fq);
;         const size_t step = (size_t)16 * ldc * 2;
; #pragma unroll
;         for (int ai = 0; ai < 2; ++ai) {
; #pragma unroll
;             for (int m = 0; m < 4; ++m) {
;                 PG8_OPQ(p);
; #pragma unroll
;                 for (int bj = 0; bj < 2; ++bj) { f32x4 v0 = acc[ai][bj][m][0], v1 = acc[ai][bj][m][1];
;                     if (ACT == 1) {
; #pragma unroll
;                         for (int j = 0; j < 4; ++j) { const float a0 = fmaxf(v0[j], 0.f), a1 = fmaxf(v1[j], 0.f); v0[j] = a0 * a0; v1[j] = a1 * a1; } }
;                     u32x4 w; w.x = cvt_pk_bf16(v0[0], v0[1]); w.y = cvt_pk_bf16(v0[2], v0[3]); w.z = cvt_pk_bf16(v1[0], v1[1]); w.w = cvt_pk_bf16(v1[2], v1[3]);
;                     *(u32x4*)(p + bj * HALF * 2) = w; }
;                 p += step;
;             }
;             p += 4 * step;
;         }
;     }
.LBB0_436:
	s_cmp_lg_u32 s8, 15
	s_cbranch_scc1 .LBB0_438
	s_and_b64 vcc, exec, s[44:45]
	s_cbranch_vccz .LBB0_438
	s_barrier
.LBB0_438:
	v_max3_f32 v122, v122, v122, 0
	s_lshr_b32 s36, s8, 2
	s_lshl_b32 s36, s36, 23
	s_and_b32 s99, s8, 3
	s_lshl_b32 s99, s99, 8
	s_add_u32 s36, s36, s99
	s_lshr_b32 s99, s98, 14
	s_add_u32 s36, s36, s99
	v_max3_f32 v123, v123, v123, 0
	v_max3_f32 v124, v124, v124, 0
	v_max3_f32 v125, v125, v125, 0
	v_lshl_add_u64 v[144:145], s[36:37], 1, v[136:137]
	v_max3_f32 v126, v126, v126, 0
	v_mul_f32_e32 v122, v122, v122
	v_max3_f32 v127, v127, v127, 0
	v_max3_f32 v128, v128, v128, 0
	v_max3_f32 v129, v129, v129, 0
	v_max3_f32 v114, v114, v114, 0
	v_max3_f32 v115, v115, v115, 0
	v_max3_f32 v116, v116, v116, 0
	v_mul_f32_e32 v123, v123, v123
	v_mul_f32_e32 v124, v124, v124
	v_mul_f32_e32 v125, v125, v125
	v_cvt_pk_bf16_f32 v122, v122, v123
	v_mul_f32_e32 v126, v126, v126
	v_mul_f32_e32 v127, v127, v127
	v_mul_f32_e32 v128, v128, v128
	v_mul_f32_e32 v129, v129, v129
	v_cvt_pk_bf16_f32 v123, v124, v125
	v_cvt_pk_bf16_f32 v124, v126, v127
	v_cvt_pk_bf16_f32 v125, v128, v129
	global_store_dwordx4 v[144:145], v[122:125], off
	v_max3_f32 v118, v118, v118, 0
	v_max3_f32 v117, v117, v117, 0
	v_mul_f32_e32 v122, v114, v114
	v_max3_f32 v114, v119, v119, 0
	v_mul_f32_e32 v119, v115, v115
	v_max3_f32 v115, v120, v120, 0
	v_mul_f32_e32 v120, v116, v116
	v_max3_f32 v116, v121, v121, 0
	v_mul_f32_e32 v114, v114, v114
	v_mul_f32_e32 v115, v115, v115
	v_mul_f32_e32 v116, v116, v116
	v_max3_f32 v106, v106, v106, 0
	v_mul_f32_e32 v118, v118, v118
	v_mul_f32_e32 v117, v117, v117
	v_cvt_pk_bf16_f32 v114, v118, v114
	v_cvt_pk_bf16_f32 v115, v115, v116
	v_cvt_pk_bf16_f32 v116, v122, v119
	v_max3_f32 v107, v107, v107, 0
	v_max3_f32 v108, v108, v108, 0
	v_cvt_pk_bf16_f32 v117, v120, v117
	global_store_dwordx4 v[144:145], v[114:117], off offset:256
	s_nop 1
	v_mul_f32_e32 v116, v106, v106
	v_max3_f32 v106, v111, v111, 0
	v_max3_f32 v110, v110, v110, 0
	v_mul_f32_e32 v111, v107, v107
	v_max3_f32 v107, v112, v112, 0
	v_mul_f32_e32 v112, v108, v108
	v_max3_f32 v108, v113, v113, 0
	v_max3_f32 v109, v109, v109, 0
	v_lshl_add_u64 v[114:115], v[144:145], 0, s[16:17]
	v_mul_f32_e32 v106, v106, v106
	v_max3_f32 v98, v98, v98, 0
	v_max3_f32 v99, v99, v99, 0
	v_max3_f32 v100, v100, v100, 0
	v_mul_f32_e32 v110, v110, v110
	v_mul_f32_e32 v107, v107, v107
	v_mul_f32_e32 v108, v108, v108
	v_mul_f32_e32 v109, v109, v109
	v_cvt_pk_bf16_f32 v106, v110, v106
	v_cvt_pk_bf16_f32 v107, v107, v108
	v_cvt_pk_bf16_f32 v108, v116, v111
	v_cvt_pk_bf16_f32 v109, v112, v109
	global_store_dwordx4 v[114:115], v[106:109], off
	v_max3_f32 v102, v102, v102, 0
	v_max3_f32 v101, v101, v101, 0
	v_mul_f32_e32 v106, v98, v98
	v_max3_f32 v98, v103, v103, 0
	v_mul_f32_e32 v103, v99, v99
	v_max3_f32 v99, v104, v104, 0
	v_mul_f32_e32 v104, v100, v100
	v_max3_f32 v100, v105, v105, 0
	v_mul_f32_e32 v98, v98, v98
	v_mul_f32_e32 v99, v99, v99
	v_mul_f32_e32 v100, v100, v100
	v_max3_f32 v90, v90, v90, 0
	v_mul_f32_e32 v102, v102, v102
	v_mul_f32_e32 v101, v101, v101
	v_cvt_pk_bf16_f32 v98, v102, v98
	v_cvt_pk_bf16_f32 v99, v99, v100
	v_cvt_pk_bf16_f32 v100, v106, v103
	v_max3_f32 v91, v91, v91, 0
	v_max3_f32 v92, v92, v92, 0
	v_cvt_pk_bf16_f32 v101, v104, v101
	global_store_dwordx4 v[114:115], v[98:101], off offset:256
	s_nop 1
	v_mul_f32_e32 v100, v90, v90
	v_max3_f32 v90, v95, v95, 0
	v_max3_f32 v94, v94, v94, 0
	v_mul_f32_e32 v95, v91, v91
	v_max3_f32 v91, v96, v96, 0
	v_mul_f32_e32 v96, v92, v92
	v_max3_f32 v92, v97, v97, 0
	v_max3_f32 v93, v93, v93, 0
	v_lshl_add_u64 v[98:99], v[114:115], 0, s[16:17]
	v_mul_f32_e32 v90, v90, v90
	v_max3_f32 v82, v82, v82, 0
	v_max3_f32 v83, v83, v83, 0
	v_max3_f32 v84, v84, v84, 0
	v_mul_f32_e32 v94, v94, v94
	v_mul_f32_e32 v91, v91, v91
	v_mul_f32_e32 v92, v92, v92
	v_mul_f32_e32 v93, v93, v93
	v_cvt_pk_bf16_f32 v90, v94, v90
	v_cvt_pk_bf16_f32 v91, v91, v92
	v_cvt_pk_bf16_f32 v92, v100, v95
	v_cvt_pk_bf16_f32 v93, v96, v93
	global_store_dwordx4 v[98:99], v[90:93], off
	v_max3_f32 v86, v86, v86, 0
	v_max3_f32 v85, v85, v85, 0
	v_mul_f32_e32 v90, v82, v82
	v_max3_f32 v82, v87, v87, 0
	v_mul_f32_e32 v87, v83, v83
	v_max3_f32 v83, v88, v88, 0
	v_mul_f32_e32 v88, v84, v84
	v_max3_f32 v84, v89, v89, 0
	v_mul_f32_e32 v82, v82, v82
	v_mul_f32_e32 v83, v83, v83
	v_mul_f32_e32 v84, v84, v84
	v_max3_f32 v74, v74, v74, 0
	v_mul_f32_e32 v86, v86, v86
	v_mul_f32_e32 v85, v85, v85
	v_cvt_pk_bf16_f32 v82, v86, v82
	v_cvt_pk_bf16_f32 v83, v83, v84
	v_cvt_pk_bf16_f32 v84, v90, v87
	v_max3_f32 v75, v75, v75, 0
	v_max3_f32 v76, v76, v76, 0
	v_cvt_pk_bf16_f32 v85, v88, v85
	global_store_dwordx4 v[98:99], v[82:85], off offset:256
	s_nop 1
	v_mul_f32_e32 v84, v74, v74
	v_max3_f32 v74, v79, v79, 0
	v_max3_f32 v78, v78, v78, 0
	v_mul_f32_e32 v79, v75, v75
	v_max3_f32 v75, v80, v80, 0
	v_mul_f32_e32 v80, v76, v76
	v_max3_f32 v76, v81, v81, 0
	v_max3_f32 v77, v77, v77, 0
	v_lshl_add_u64 v[82:83], v[98:99], 0, s[16:17]
	v_mul_f32_e32 v74, v74, v74
	v_max3_f32 v66, v66, v66, 0
	v_max3_f32 v67, v67, v67, 0
	v_max3_f32 v68, v68, v68, 0
	v_mul_f32_e32 v78, v78, v78
	v_mul_f32_e32 v75, v75, v75
	v_mul_f32_e32 v76, v76, v76
	v_mul_f32_e32 v77, v77, v77
	v_cvt_pk_bf16_f32 v74, v78, v74
	v_cvt_pk_bf16_f32 v75, v75, v76
	v_cvt_pk_bf16_f32 v76, v84, v79
	v_cvt_pk_bf16_f32 v77, v80, v77
	global_store_dwordx4 v[82:83], v[74:77], off
	v_max3_f32 v70, v70, v70, 0
	v_max3_f32 v69, v69, v69, 0
	v_mul_f32_e32 v74, v66, v66
	v_max3_f32 v66, v71, v71, 0
	v_mul_f32_e32 v71, v67, v67
	v_max3_f32 v67, v72, v72, 0
	v_mul_f32_e32 v72, v68, v68
	v_max3_f32 v68, v73, v73, 0
	v_mul_f32_e32 v66, v66, v66
; __device__ __forceinline__ unsigned cvt_pk_bf16(float lo, float hi) { unsigned r; asm volatile("v_cvt_pk_bf16_f32 %0, %1, %2" : "=v"(r) : "v"(lo), "v"(hi)); return r; }
; #define PG8_BAR __builtin_amdgcn_s_barrier()
; #define PG8_OPQ(p) asm volatile("" : "+v"(p))
; template <class Epi, class Sched>
; __device__ __forceinline__ void gemm_phase(LAS unsigned char* lds, const Gemm g, const Sched& S, const Epi& E) {
;     ...
;         if (wr == 0) PG8_BAR;
;         E(acc, cur, wr, wc, fr, fq); S.done(cur);
;         if (!has_next) break;
; #pragma unroll
;         for (int a = 0; a < 2; ++a)
; #pragma unroll
;             for (int b = 0; b < 2; ++b)
; #pragma unroll
;                 for (int m = 0; m < 4; ++m)
; #pragma unroll
;                     for (int n = 0; n < 2; ++n) acc[a][b][m][n] = (f32x4){0.f, 0.f, 0.f, 0.f};
;         cur = nxt; cA = nA; cB = nB; ++ui;
;         if (wr == 1) PG8_BAR;
;     __device__ __forceinline__ void operator()(const f32x4 (&acc)[2][2][4][2], const Unit& u, int wr, int wc, int fr, int fq) const {
;     ...
;             for (int m = 0; m < 4; ++m) {
;                 PG8_OPQ(p);
; #pragma unroll
;                 for (int bj = 0; bj < 2; ++bj) { f32x4 v0 = acc[ai][bj][m][0], v1 = acc[ai][bj][m][1];
;                     if (ACT == 1) {
; #pragma unroll
;                         for (int j = 0; j < 4; ++j) { const float a0 = fmaxf(v0[j], 0.f), a1 = fmaxf(v1[j], 0.f); v0[j] = a0 * a0; v1[j] = a1 * a1; } }
;                     u32x4 w; w.x = cvt_pk_bf16(v0[0], v0[1]); w.y = cvt_pk_bf16(v0[2], v0[3]); w.z = cvt_pk_bf16(v1[0], v1[1]); w.w = cvt_pk_bf16(v1[2], v1[3]);
;                     *(u32x4*)(p + bj * HALF * 2) = w; }
;                 p += step;
;             }
;             p += 4 * step;
;         }
;     }
	v_mul_f32_e32 v67, v67, v67
	v_mul_f32_e32 v68, v68, v68
	v_max3_f32 v58, v58, v58, 0
	v_mul_f32_e32 v70, v70, v70
	v_mul_f32_e32 v69, v69, v69
	v_cvt_pk_bf16_f32 v66, v70, v66
	v_cvt_pk_bf16_f32 v67, v67, v68
	v_cvt_pk_bf16_f32 v68, v74, v71
	v_max3_f32 v59, v59, v59, 0
	v_max3_f32 v60, v60, v60, 0
	v_cvt_pk_bf16_f32 v69, v72, v69
	global_store_dwordx4 v[82:83], v[66:69], off offset:256
	s_nop 1
	v_mul_f32_e32 v68, v58, v58
	v_max3_f32 v58, v63, v63, 0
	s_mov_b64 s[48:49], 0xa0000
	v_max3_f32 v62, v62, v62, 0
	v_mul_f32_e32 v63, v59, v59
	v_max3_f32 v59, v64, v64, 0
	v_mul_f32_e32 v64, v60, v60
	v_max3_f32 v60, v65, v65, 0
	v_max3_f32 v61, v61, v61, 0
	v_lshl_add_u64 v[66:67], v[82:83], 0, s[48:49]
	v_mul_f32_e32 v58, v58, v58
	v_max3_f32 v50, v50, v50, 0
	v_max3_f32 v51, v51, v51, 0
	v_max3_f32 v52, v52, v52, 0
	v_mul_f32_e32 v62, v62, v62
	v_mul_f32_e32 v59, v59, v59
	v_mul_f32_e32 v60, v60, v60
	v_mul_f32_e32 v61, v61, v61
	v_cvt_pk_bf16_f32 v58, v62, v58
	v_cvt_pk_bf16_f32 v59, v59, v60
	v_cvt_pk_bf16_f32 v60, v68, v63
	v_cvt_pk_bf16_f32 v61, v64, v61
	global_store_dwordx4 v[66:67], v[58:61], off
	v_max3_f32 v54, v54, v54, 0
	v_max3_f32 v53, v53, v53, 0
	v_mul_f32_e32 v58, v50, v50
	v_max3_f32 v50, v55, v55, 0
	v_mul_f32_e32 v55, v51, v51
	v_max3_f32 v51, v56, v56, 0
	v_mul_f32_e32 v56, v52, v52
	v_max3_f32 v52, v57, v57, 0
	v_mul_f32_e32 v50, v50, v50
	v_mul_f32_e32 v51, v51, v51
	v_mul_f32_e32 v52, v52, v52
	v_max3_f32 v42, v42, v42, 0
	v_mul_f32_e32 v54, v54, v54
	v_mul_f32_e32 v53, v53, v53
	v_cvt_pk_bf16_f32 v50, v54, v50
	v_cvt_pk_bf16_f32 v51, v51, v52
	v_cvt_pk_bf16_f32 v52, v58, v55
	v_max3_f32 v43, v43, v43, 0
	v_max3_f32 v44, v44, v44, 0
	v_cvt_pk_bf16_f32 v53, v56, v53
	global_store_dwordx4 v[66:67], v[50:53], off offset:256
	s_nop 1
	v_mul_f32_e32 v52, v42, v42
	v_max3_f32 v42, v47, v47, 0
	v_max3_f32 v46, v46, v46, 0
	v_mul_f32_e32 v47, v43, v43
	v_max3_f32 v43, v48, v48, 0
	v_mul_f32_e32 v48, v44, v44
	v_max3_f32 v44, v49, v49, 0
	v_max3_f32 v45, v45, v45, 0
	v_lshl_add_u64 v[50:51], v[66:67], 0, s[16:17]
	v_mul_f32_e32 v42, v42, v42
	v_max3_f32 v34, v34, v34, 0
	v_max3_f32 v35, v35, v35, 0
	v_max3_f32 v36, v36, v36, 0
	v_mul_f32_e32 v46, v46, v46
	v_mul_f32_e32 v43, v43, v43
	v_mul_f32_e32 v44, v44, v44
	v_mul_f32_e32 v45, v45, v45
	v_cvt_pk_bf16_f32 v42, v46, v42
	v_cvt_pk_bf16_f32 v43, v43, v44
	v_cvt_pk_bf16_f32 v44, v52, v47
	v_cvt_pk_bf16_f32 v45, v48, v45
	global_store_dwordx4 v[50:51], v[42:45], off
	v_max3_f32 v38, v38, v38, 0
	v_max3_f32 v37, v37, v37, 0
	v_mul_f32_e32 v42, v34, v34
	v_max3_f32 v34, v39, v39, 0
	v_mul_f32_e32 v39, v35, v35
	v_max3_f32 v35, v40, v40, 0
	v_mul_f32_e32 v40, v36, v36
	v_max3_f32 v36, v41, v41, 0
	v_mul_f32_e32 v34, v34, v34
	v_mul_f32_e32 v35, v35, v35
	v_mul_f32_e32 v36, v36, v36
	v_max3_f32 v26, v26, v26, 0
	v_mul_f32_e32 v38, v38, v38
	v_mul_f32_e32 v37, v37, v37
	v_cvt_pk_bf16_f32 v34, v38, v34
	v_cvt_pk_bf16_f32 v35, v35, v36
	v_cvt_pk_bf16_f32 v36, v42, v39
	v_max3_f32 v27, v27, v27, 0
	v_max3_f32 v28, v28, v28, 0
	v_cvt_pk_bf16_f32 v37, v40, v37
	global_store_dwordx4 v[50:51], v[34:37], off offset:256
	s_nop 1
	v_mul_f32_e32 v36, v26, v26
	v_max3_f32 v26, v31, v31, 0
	v_max3_f32 v30, v30, v30, 0
	v_mul_f32_e32 v31, v27, v27
	v_max3_f32 v27, v32, v32, 0
	v_mul_f32_e32 v32, v28, v28
	v_max3_f32 v28, v33, v33, 0
	v_max3_f32 v29, v29, v29, 0
	v_lshl_add_u64 v[34:35], v[50:51], 0, s[16:17]
	v_mul_f32_e32 v26, v26, v26
	v_max3_f32 v18, v18, v18, 0
	v_max3_f32 v19, v19, v19, 0
	v_max3_f32 v20, v20, v20, 0
	v_mul_f32_e32 v30, v30, v30
	v_mul_f32_e32 v27, v27, v27
	v_mul_f32_e32 v28, v28, v28
	v_mul_f32_e32 v29, v29, v29
	v_cvt_pk_bf16_f32 v26, v30, v26
	v_cvt_pk_bf16_f32 v27, v27, v28
	v_cvt_pk_bf16_f32 v28, v36, v31
	v_cvt_pk_bf16_f32 v29, v32, v29
	global_store_dwordx4 v[34:35], v[26:29], off
	v_max3_f32 v22, v22, v22, 0
	v_max3_f32 v21, v21, v21, 0
	v_mul_f32_e32 v26, v18, v18
	v_max3_f32 v18, v23, v23, 0
	v_mul_f32_e32 v23, v19, v19
	v_max3_f32 v19, v24, v24, 0
	v_mul_f32_e32 v24, v20, v20
	v_max3_f32 v20, v25, v25, 0
	v_mul_f32_e32 v18, v18, v18
	v_mul_f32_e32 v19, v19, v19
	v_mul_f32_e32 v20, v20, v20
	v_max3_f32 v10, v10, v10, 0
	v_mul_f32_e32 v22, v22, v22
	v_mul_f32_e32 v21, v21, v21
	v_cvt_pk_bf16_f32 v18, v22, v18
	v_cvt_pk_bf16_f32 v19, v19, v20
	v_cvt_pk_bf16_f32 v20, v26, v23
	v_max3_f32 v11, v11, v11, 0
	v_max3_f32 v12, v12, v12, 0
	v_cvt_pk_bf16_f32 v21, v24, v21
	global_store_dwordx4 v[34:35], v[18:21], off offset:256
	s_nop 1
	v_mul_f32_e32 v20, v10, v10
	v_max3_f32 v10, v15, v15, 0
	v_max3_f32 v14, v14, v14, 0
	v_mul_f32_e32 v15, v11, v11
	v_max3_f32 v11, v16, v16, 0
	v_mul_f32_e32 v16, v12, v12
	v_max3_f32 v12, v17, v17, 0
	v_max3_f32 v13, v13, v13, 0
	v_lshl_add_u64 v[18:19], v[34:35], 0, s[16:17]
	v_mul_f32_e32 v10, v10, v10
	v_max3_f32 v2, v2, v2, 0
	v_max3_f32 v3, v3, v3, 0
	v_max3_f32 v4, v4, v4, 0
	v_mul_f32_e32 v14, v14, v14
	v_mul_f32_e32 v11, v11, v11
	v_mul_f32_e32 v12, v12, v12
	v_mul_f32_e32 v13, v13, v13
	v_cvt_pk_bf16_f32 v10, v14, v10
	v_cvt_pk_bf16_f32 v11, v11, v12
	v_cvt_pk_bf16_f32 v12, v20, v15
	v_cvt_pk_bf16_f32 v13, v16, v13
	global_store_dwordx4 v[18:19], v[10:13], off
	v_max3_f32 v5, v5, v5, 0
	v_max3_f32 v6, v6, v6, 0
	v_mul_f32_e32 v10, v2, v2
	v_max3_f32 v2, v7, v7, 0
	v_mul_f32_e32 v7, v3, v3
	v_max3_f32 v3, v8, v8, 0
	v_mul_f32_e32 v8, v4, v4
	v_max3_f32 v4, v9, v9, 0
	v_mul_f32_e32 v2, v2, v2
	v_mul_f32_e32 v3, v3, v3
	v_mul_f32_e32 v4, v4, v4
	v_mul_f32_e32 v5, v5, v5
	s_cmp_eq_u32 s8, 15
	s_mov_b64 s[8:9], -1
	v_mul_f32_e32 v6, v6, v6
	v_cvt_pk_bf16_f32 v2, v6, v2
	v_cvt_pk_bf16_f32 v3, v3, v4
	v_cvt_pk_bf16_f32 v4, v10, v7
	v_cvt_pk_bf16_f32 v5, v8, v5
	global_store_dwordx4 v[18:19], v[2:5], off offset:256
	s_cbranch_scc1 .LBB0_430
	s_andn2_b64 vcc, exec, s[38:39]
	s_cbranch_vccnz .LBB0_429
	s_branch .LBB0_429

; __device__ __forceinline__ float bflo_(unsigned w) { return __uint_as_float(w << 16); }
; __device__ __forceinline__ float bfhi_(unsigned w) { return __uint_as_float(w & 0xffff0000u); }
; __device__ __forceinline__ unsigned cvt_pk_bf16(float lo, float hi) { unsigned r; asm volatile("v_cvt_pk_bf16_f32 %0, %1, %2" : "=v"(r) : "v"(lo), "v"(hi)); return r; }
; #define PG8_BAR __builtin_amdgcn_s_barrier()
; #define PG8_OPQ(p) asm volatile("" : "+v"(p))
; template <class Epi, class Sched>
; __device__ __forceinline__ void gemm_phase(LAS unsigned char* lds, const Gemm g, const Sched& S, const Epi& E) {
;     ...
;         if (wr == 0) PG8_BAR;
;         E(acc, cur, wr, wc, fr, fq); S.done(cur);
;     __device__ __forceinline__ void operator()(const f32x4 (&acc)[2][2][4][2], const Unit& u, int wr, int wc, int fr, int fq) const {
;         char* p = (char*)(HB + (size_t)(wr * 64 + fr) * ldc + u.pn * BM + wc * 32 + 8 * fq);
;         const size_t step = (size_t)16 * ldc * 2;
; #pragma unroll
;         for (int ai = 0; ai < 2; ++ai) {
;             PG8_OPQ(p);
;             u32x4 h[4][2];
; #pragma unroll
;             for (int m = 0; m < 4; ++m)
; #pragma unroll
;                 for (int bj = 0; bj < 2; ++bj) h[m][bj] = *(const u32x4*)(p + m * step + bj * HALF * 2);
; #pragma unroll
;             for (int m = 0; m < 4; ++m)
; #pragma unroll
;                 for (int bj = 0; bj < 2; ++bj) { const f32x4 v0 = acc[ai][bj][m][0], v1 = acc[ai][bj][m][1]; const u32x4 hh = h[m][bj];
;                     u32x4 w;
;                     w.x = cvt_pk_bf16(bflo_(hh.x) * alpha + v0[0], bfhi_(hh.x) * alpha + v0[1]); w.y = cvt_pk_bf16(bflo_(hh.y) * alpha + v0[2], bfhi_(hh.y) * alpha + v0[3]);
;                     w.z = cvt_pk_bf16(bflo_(hh.z) * alpha + v1[0], bfhi_(hh.z) * alpha + v1[1]); w.w = cvt_pk_bf16(bflo_(hh.w) * alpha + v1[2], bfhi_(hh.w) * alpha + v1[3]);
;                     *(u32x4*)(p + m * step + bj * HALF * 2) = w; }
;             p += 8 * step;
;         }
.LBB0_451:
	s_cmp_lg_u32 s8, 3
	s_cbranch_scc1 .LBB0_453
	s_and_b64 vcc, exec, s[42:43]
	s_cbranch_vccz .LBB0_453
	s_barrier
.LBB0_453:
	s_sub_u32 s36, 3, s8
	s_lshl_b32 s36, s36, 21
	v_lshl_add_u64 v[154:155], s[36:37], 1, v[148:149]
	global_load_dwordx4 v[162:165], v[154:155], off
	global_load_dwordx4 v[166:169], v[154:155], off offset:256
	v_add_co_u32_e32 v182, vcc, 0x8000, v154
	s_cmp_eq_u32 s8, 3
	s_nop 0
	v_addc_co_u32_e32 v183, vcc, 0, v155, vcc
	global_load_dwordx4 v[170:173], v[182:183], off
	global_load_dwordx4 v[174:177], v[182:183], off offset:256
	v_add_co_u32_e32 v158, vcc, 0x10000, v154
	s_mov_b64 s[8:9], -1
	s_nop 0
	v_addc_co_u32_e32 v159, vcc, 0, v155, vcc
	global_load_dwordx4 v[178:181], v[158:159], off
	global_load_dwordx4 v[138:141], v[158:159], off offset:256
	v_add_co_u32_e32 v156, vcc, 0x18000, v154
	s_waitcnt vmcnt(0) lgkmcnt(0)
	v_lshlrev_b32_e32 v184, 16, v162
	v_addc_co_u32_e32 v157, vcc, 0, v155, vcc
	global_load_dwordx4 v[134:137], v[156:157], off
	global_load_dwordx4 v[130:133], v[156:157], off offset:256
	v_and_b32_e32 v162, 0xffff0000, v162
	v_lshlrev_b32_e32 v185, 16, v163
	v_and_b32_e32 v163, 0xffff0000, v163
	v_lshlrev_b32_e32 v186, 16, v164
	v_and_b32_e32 v164, 0xffff0000, v164
	v_lshlrev_b32_e32 v187, 16, v165
	v_and_b32_e32 v165, 0xffff0000, v165
	v_fmac_f32_e32 v122, 0x3fb504f3, v184
	v_fmac_f32_e32 v123, 0x3fb504f3, v162
	v_fmac_f32_e32 v124, 0x3fb504f3, v185
	v_fmac_f32_e32 v125, 0x3fb504f3, v163
	v_fmac_f32_e32 v126, 0x3fb504f3, v186
	v_fmac_f32_e32 v127, 0x3fb504f3, v164
	v_fmac_f32_e32 v128, 0x3fb504f3, v187
	v_lshlrev_b32_e32 v188, 16, v166
	v_and_b32_e32 v166, 0xffff0000, v166
	v_lshlrev_b32_e32 v190, 16, v167
	v_and_b32_e32 v167, 0xffff0000, v167
	v_fmac_f32_e32 v129, 0x3fb504f3, v165
	v_cvt_pk_bf16_f32 v122, v122, v123
	v_cvt_pk_bf16_f32 v123, v124, v125
	v_cvt_pk_bf16_f32 v124, v126, v127
	v_cvt_pk_bf16_f32 v125, v128, v129
	v_lshlrev_b32_e32 v126, 16, v170
	v_and_b32_e32 v127, 0xffff0000, v170
	v_lshlrev_b32_e32 v128, 16, v171
	v_lshlrev_b32_e32 v162, 16, v172
	v_lshlrev_b32_e32 v192, 16, v168
	v_and_b32_e32 v168, 0xffff0000, v168
	v_lshlrev_b32_e32 v193, 16, v169
	v_and_b32_e32 v169, 0xffff0000, v169
	v_fmac_f32_e32 v118, 0x3fb504f3, v188
	v_fmac_f32_e32 v119, 0x3fb504f3, v166
	v_fmac_f32_e32 v120, 0x3fb504f3, v190
	v_fmac_f32_e32 v121, 0x3fb504f3, v167
	v_and_b32_e32 v129, 0xffff0000, v171
	v_and_b32_e32 v163, 0xffff0000, v172
	v_fmac_f32_e32 v110, 0x3fb504f3, v126
	v_fmac_f32_e32 v111, 0x3fb504f3, v127
	v_fmac_f32_e32 v112, 0x3fb504f3, v128
	v_fmac_f32_e32 v106, 0x3fb504f3, v162
	v_fmac_f32_e32 v114, 0x3fb504f3, v192
	v_fmac_f32_e32 v115, 0x3fb504f3, v168
	v_fmac_f32_e32 v116, 0x3fb504f3, v193
	v_fmac_f32_e32 v117, 0x3fb504f3, v169
	global_store_dwordx4 v[154:155], v[122:125], off
	v_cvt_pk_bf16_f32 v118, v118, v119
	v_cvt_pk_bf16_f32 v119, v120, v121
	v_cvt_pk_bf16_f32 v120, v114, v115
	v_cvt_pk_bf16_f32 v121, v116, v117
	v_fmac_f32_e32 v113, 0x3fb504f3, v129
	v_fmac_f32_e32 v107, 0x3fb504f3, v163
	global_store_dwordx4 v[154:155], v[118:121], off offset:256
	v_cvt_pk_bf16_f32 v110, v110, v111
	v_cvt_pk_bf16_f32 v111, v112, v113
	v_cvt_pk_bf16_f32 v112, v106, v107
	v_lshlrev_b32_e32 v106, 16, v174
	v_fmac_f32_e32 v102, 0x3fb504f3, v106
	v_and_b32_e32 v106, 0xffff0000, v174
	v_lshlrev_b32_e32 v164, 16, v173
	v_and_b32_e32 v165, 0xffff0000, v173
	v_fmac_f32_e32 v103, 0x3fb504f3, v106
	v_fmac_f32_e32 v108, 0x3fb504f3, v164
	v_fmac_f32_e32 v109, 0x3fb504f3, v165
	v_cvt_pk_bf16_f32 v113, v108, v109
	global_store_dwordx4 v[182:183], v[110:113], off
	v_cvt_pk_bf16_f32 v102, v102, v103
	v_lshlrev_b32_e32 v103, 16, v175
	v_fmac_f32_e32 v104, 0x3fb504f3, v103
	v_and_b32_e32 v103, 0xffff0000, v175
	v_fmac_f32_e32 v105, 0x3fb504f3, v103
	v_cvt_pk_bf16_f32 v103, v104, v105
	v_lshlrev_b32_e32 v104, 16, v176
	v_fmac_f32_e32 v98, 0x3fb504f3, v104
	v_and_b32_e32 v104, 0xffff0000, v176
	v_fmac_f32_e32 v99, 0x3fb504f3, v104
	v_cvt_pk_bf16_f32 v104, v98, v99
	v_lshlrev_b32_e32 v98, 16, v177
	v_fmac_f32_e32 v100, 0x3fb504f3, v98
	v_and_b32_e32 v98, 0xffff0000, v177
	v_fmac_f32_e32 v101, 0x3fb504f3, v98
	v_lshlrev_b32_e32 v98, 16, v178
	v_fmac_f32_e32 v94, 0x3fb504f3, v98
	v_and_b32_e32 v98, 0xffff0000, v178
	v_fmac_f32_e32 v95, 0x3fb504f3, v98
	v_cvt_pk_bf16_f32 v105, v100, v101
	global_store_dwordx4 v[182:183], v[102:105], off offset:256
	v_cvt_pk_bf16_f32 v94, v94, v95
	v_lshlrev_b32_e32 v95, 16, v179
	v_fmac_f32_e32 v96, 0x3fb504f3, v95
	v_and_b32_e32 v95, 0xffff0000, v179
	v_fmac_f32_e32 v97, 0x3fb504f3, v95
	v_cvt_pk_bf16_f32 v95, v96, v97
	v_lshlrev_b32_e32 v96, 16, v180
	v_fmac_f32_e32 v90, 0x3fb504f3, v96
	v_and_b32_e32 v96, 0xffff0000, v180
	v_fmac_f32_e32 v91, 0x3fb504f3, v96
	v_cvt_pk_bf16_f32 v96, v90, v91
	v_lshlrev_b32_e32 v90, 16, v181
	v_fmac_f32_e32 v92, 0x3fb504f3, v90
	v_and_b32_e32 v90, 0xffff0000, v181
	v_fmac_f32_e32 v93, 0x3fb504f3, v90
	v_lshlrev_b32_e32 v90, 16, v138
	v_fmac_f32_e32 v86, 0x3fb504f3, v90
	v_and_b32_e32 v90, 0xffff0000, v138
	v_fmac_f32_e32 v87, 0x3fb504f3, v90
	v_cvt_pk_bf16_f32 v97, v92, v93
	global_store_dwordx4 v[158:159], v[94:97], off
	v_cvt_pk_bf16_f32 v86, v86, v87
	v_lshlrev_b32_e32 v87, 16, v139
	v_fmac_f32_e32 v88, 0x3fb504f3, v87
	v_and_b32_e32 v87, 0xffff0000, v139
	v_fmac_f32_e32 v89, 0x3fb504f3, v87
	v_cvt_pk_bf16_f32 v87, v88, v89
	v_lshlrev_b32_e32 v88, 16, v140
	v_fmac_f32_e32 v82, 0x3fb504f3, v88
	v_and_b32_e32 v88, 0xffff0000, v140
	v_fmac_f32_e32 v83, 0x3fb504f3, v88
	v_cvt_pk_bf16_f32 v88, v82, v83
	v_lshlrev_b32_e32 v82, 16, v141
	v_fmac_f32_e32 v84, 0x3fb504f3, v82
	v_and_b32_e32 v82, 0xffff0000, v141
	v_fmac_f32_e32 v85, 0x3fb504f3, v82
	s_waitcnt vmcnt(5) lgkmcnt(0)
; __device__ __forceinline__ float bflo_(unsigned w) { return __uint_as_float(w << 16); }
; __device__ __forceinline__ float bfhi_(unsigned w) { return __uint_as_float(w & 0xffff0000u); }
; __device__ __forceinline__ unsigned cvt_pk_bf16(float lo, float hi) { unsigned r; asm volatile("v_cvt_pk_bf16_f32 %0, %1, %2" : "=v"(r) : "v"(lo), "v"(hi)); return r; }
; #define PG8_OPQ(p) asm volatile("" : "+v"(p))
;     __device__ __forceinline__ void operator()(const f32x4 (&acc)[2][2][4][2], const Unit& u, int wr, int wc, int fr, int fq) const {
;     ...
;         for (int ai = 0; ai < 2; ++ai) {
;             PG8_OPQ(p);
;             u32x4 h[4][2];
; #pragma unroll
;             for (int m = 0; m < 4; ++m)
; #pragma unroll
;                 for (int bj = 0; bj < 2; ++bj) h[m][bj] = *(const u32x4*)(p + m * step + bj * HALF * 2);
; #pragma unroll
;             for (int m = 0; m < 4; ++m)
; #pragma unroll
;                 for (int bj = 0; bj < 2; ++bj) { const f32x4 v0 = acc[ai][bj][m][0], v1 = acc[ai][bj][m][1]; const u32x4 hh = h[m][bj];
;                     u32x4 w;
;                     w.x = cvt_pk_bf16(bflo_(hh.x) * alpha + v0[0], bfhi_(hh.x) * alpha + v0[1]); w.y = cvt_pk_bf16(bflo_(hh.y) * alpha + v0[2], bfhi_(hh.y) * alpha + v0[3]);
;                     w.z = cvt_pk_bf16(bflo_(hh.z) * alpha + v1[0], bfhi_(hh.z) * alpha + v1[1]); w.w = cvt_pk_bf16(bflo_(hh.w) * alpha + v1[2], bfhi_(hh.w) * alpha + v1[3]);
;                     *(u32x4*)(p + m * step + bj * HALF * 2) = w; }
;             p += 8 * step;
;         }
	v_lshlrev_b32_e32 v82, 16, v134
	v_fmac_f32_e32 v78, 0x3fb504f3, v82
	v_and_b32_e32 v82, 0xffff0000, v134
	v_fmac_f32_e32 v79, 0x3fb504f3, v82
	v_cvt_pk_bf16_f32 v89, v84, v85
	global_store_dwordx4 v[158:159], v[86:89], off offset:256
	v_cvt_pk_bf16_f32 v78, v78, v79
	v_lshlrev_b32_e32 v79, 16, v135
	v_fmac_f32_e32 v80, 0x3fb504f3, v79
	v_and_b32_e32 v79, 0xffff0000, v135
	v_fmac_f32_e32 v81, 0x3fb504f3, v79
	v_cvt_pk_bf16_f32 v79, v80, v81
	v_lshlrev_b32_e32 v80, 16, v136
	v_fmac_f32_e32 v74, 0x3fb504f3, v80
	v_and_b32_e32 v80, 0xffff0000, v136
	v_fmac_f32_e32 v75, 0x3fb504f3, v80
	v_cvt_pk_bf16_f32 v80, v74, v75
	v_lshlrev_b32_e32 v74, 16, v137
	v_fmac_f32_e32 v76, 0x3fb504f3, v74
	v_and_b32_e32 v74, 0xffff0000, v137
	v_fmac_f32_e32 v77, 0x3fb504f3, v74
	v_lshlrev_b32_e32 v74, 16, v130
	v_fmac_f32_e32 v70, 0x3fb504f3, v74
	v_and_b32_e32 v74, 0xffff0000, v130
	v_fmac_f32_e32 v71, 0x3fb504f3, v74
	v_cvt_pk_bf16_f32 v81, v76, v77
	global_store_dwordx4 v[156:157], v[78:81], off
	v_cvt_pk_bf16_f32 v70, v70, v71
	v_lshlrev_b32_e32 v71, 16, v131
	v_fmac_f32_e32 v72, 0x3fb504f3, v71
	v_and_b32_e32 v71, 0xffff0000, v131
	v_fmac_f32_e32 v73, 0x3fb504f3, v71
	v_cvt_pk_bf16_f32 v71, v72, v73
	v_lshlrev_b32_e32 v72, 16, v132
	v_fmac_f32_e32 v66, 0x3fb504f3, v72
	v_and_b32_e32 v72, 0xffff0000, v132
	v_fmac_f32_e32 v67, 0x3fb504f3, v72
	v_cvt_pk_bf16_f32 v72, v66, v67
	v_lshlrev_b32_e32 v66, 16, v133
	v_fmac_f32_e32 v68, 0x3fb504f3, v66
	v_and_b32_e32 v66, 0xffff0000, v133
	v_lshl_add_u64 v[100:101], v[154:155], 0, s[24:25]
	v_fmac_f32_e32 v69, 0x3fb504f3, v66
	v_cvt_pk_bf16_f32 v73, v68, v69
	global_store_dwordx4 v[156:157], v[70:73], off offset:256
	global_load_dwordx4 v[72:75], v[100:101], off
	global_load_dwordx4 v[76:79], v[100:101], off offset:256
	v_add_co_u32_e32 v102, vcc, s87, v100
	s_waitcnt vmcnt(0) lgkmcnt(0)
	v_lshlrev_b32_e32 v106, 16, v72
	v_addc_co_u32_e32 v103, vcc, 0, v101, vcc
	global_load_dwordx4 v[80:83], v[102:103], off
	global_load_dwordx4 v[84:87], v[102:103], off offset:256
	v_add_co_u32_e32 v104, vcc, s91, v100
	v_and_b32_e32 v72, 0xffff0000, v72
	s_nop 0
	v_addc_co_u32_e32 v105, vcc, 0, v101, vcc
	global_load_dwordx4 v[88:91], v[104:105], off
	global_load_dwordx4 v[92:95], v[104:105], off offset:256
	v_add_co_u32_e32 v70, vcc, s86, v100
	v_fmac_f32_e32 v62, 0x3fb504f3, v106
	s_nop 0
	v_addc_co_u32_e32 v71, vcc, 0, v101, vcc
	global_load_dwordx4 v[96:99], v[70:71], off
	global_load_dwordx4 v[66:69], v[70:71], off offset:256
	v_fmac_f32_e32 v63, 0x3fb504f3, v72
	v_cvt_pk_bf16_f32 v62, v62, v63
	v_lshlrev_b32_e32 v63, 16, v73
	v_fmac_f32_e32 v64, 0x3fb504f3, v63
	v_and_b32_e32 v63, 0xffff0000, v73
	v_fmac_f32_e32 v65, 0x3fb504f3, v63
	v_cvt_pk_bf16_f32 v63, v64, v65
	v_lshlrev_b32_e32 v64, 16, v74
	v_fmac_f32_e32 v58, 0x3fb504f3, v64
	v_and_b32_e32 v64, 0xffff0000, v74
	v_fmac_f32_e32 v59, 0x3fb504f3, v64
	v_cvt_pk_bf16_f32 v64, v58, v59
	v_lshlrev_b32_e32 v58, 16, v75
	v_fmac_f32_e32 v60, 0x3fb504f3, v58
	v_and_b32_e32 v58, 0xffff0000, v75
	v_fmac_f32_e32 v61, 0x3fb504f3, v58
	v_lshlrev_b32_e32 v58, 16, v76
	v_fmac_f32_e32 v54, 0x3fb504f3, v58
	v_and_b32_e32 v58, 0xffff0000, v76
	v_fmac_f32_e32 v55, 0x3fb504f3, v58
	v_cvt_pk_bf16_f32 v65, v60, v61
	global_store_dwordx4 v[100:101], v[62:65], off
	v_cvt_pk_bf16_f32 v54, v54, v55
	v_lshlrev_b32_e32 v55, 16, v77
	v_fmac_f32_e32 v56, 0x3fb504f3, v55
	v_and_b32_e32 v55, 0xffff0000, v77
	v_fmac_f32_e32 v57, 0x3fb504f3, v55
	v_cvt_pk_bf16_f32 v55, v56, v57
	v_lshlrev_b32_e32 v56, 16, v78
	v_fmac_f32_e32 v50, 0x3fb504f3, v56
	v_and_b32_e32 v56, 0xffff0000, v78
	v_fmac_f32_e32 v51, 0x3fb504f3, v56
	v_cvt_pk_bf16_f32 v56, v50, v51
	v_lshlrev_b32_e32 v50, 16, v79
	v_fmac_f32_e32 v52, 0x3fb504f3, v50
	v_and_b32_e32 v50, 0xffff0000, v79
	v_fmac_f32_e32 v53, 0x3fb504f3, v50
	v_cvt_pk_bf16_f32 v57, v52, v53
	global_store_dwordx4 v[100:101], v[54:57], off offset:256
	s_waitcnt vmcnt(2) lgkmcnt(0)
; __device__ __forceinline__ float bflo_(unsigned w) { return __uint_as_float(w << 16); }
; __device__ __forceinline__ float bfhi_(unsigned w) { return __uint_as_float(w & 0xffff0000u); }
; __device__ __forceinline__ unsigned cvt_pk_bf16(float lo, float hi) { unsigned r; asm volatile("v_cvt_pk_bf16_f32 %0, %1, %2" : "=v"(r) : "v"(lo), "v"(hi)); return r; }
; #define PG8_BAR __builtin_amdgcn_s_barrier()
; #define PG8_OPQ(p) asm volatile("" : "+v"(p))
; template <class Epi, class Sched>
; __device__ __forceinline__ void gemm_phase(LAS unsigned char* lds, const Gemm g, const Sched& S, const Epi& E) {
;     ...
;         if (wr == 0) PG8_BAR;
;         E(acc, cur, wr, wc, fr, fq); S.done(cur);
;         if (!has_next) break;
; #pragma unroll
;         for (int a = 0; a < 2; ++a)
; #pragma unroll
;             for (int b = 0; b < 2; ++b)
; #pragma unroll
;                 for (int m = 0; m < 4; ++m)
; #pragma unroll
;                     for (int n = 0; n < 2; ++n) acc[a][b][m][n] = (f32x4){0.f, 0.f, 0.f, 0.f};
;         cur = nxt; cA = nA; cB = nB; ++ui;
;         if (wr == 1) PG8_BAR;
;     __device__ __forceinline__ void operator()(const f32x4 (&acc)[2][2][4][2], const Unit& u, int wr, int wc, int fr, int fq) const {
;     ...
;         for (int ai = 0; ai < 2; ++ai) {
;             PG8_OPQ(p);
;             u32x4 h[4][2];
; #pragma unroll
;             for (int m = 0; m < 4; ++m)
; #pragma unroll
;                 for (int bj = 0; bj < 2; ++bj) h[m][bj] = *(const u32x4*)(p + m * step + bj * HALF * 2);
; #pragma unroll
;             for (int m = 0; m < 4; ++m)
; #pragma unroll
;                 for (int bj = 0; bj < 2; ++bj) { const f32x4 v0 = acc[ai][bj][m][0], v1 = acc[ai][bj][m][1]; const u32x4 hh = h[m][bj];
;                     u32x4 w;
;                     w.x = cvt_pk_bf16(bflo_(hh.x) * alpha + v0[0], bfhi_(hh.x) * alpha + v0[1]); w.y = cvt_pk_bf16(bflo_(hh.y) * alpha + v0[2], bfhi_(hh.y) * alpha + v0[3]);
;                     w.z = cvt_pk_bf16(bflo_(hh.z) * alpha + v1[0], bfhi_(hh.z) * alpha + v1[1]); w.w = cvt_pk_bf16(bflo_(hh.w) * alpha + v1[2], bfhi_(hh.w) * alpha + v1[3]);
;                     *(u32x4*)(p + m * step + bj * HALF * 2) = w; }
;             p += 8 * step;
;         }
	v_lshlrev_b32_e32 v50, 16, v80
	v_fmac_f32_e32 v46, 0x3fb504f3, v50
	v_and_b32_e32 v50, 0xffff0000, v80
	v_fmac_f32_e32 v47, 0x3fb504f3, v50
	v_cvt_pk_bf16_f32 v46, v46, v47
	v_lshlrev_b32_e32 v47, 16, v81
	v_fmac_f32_e32 v48, 0x3fb504f3, v47
	v_and_b32_e32 v47, 0xffff0000, v81
	v_fmac_f32_e32 v49, 0x3fb504f3, v47
	v_cvt_pk_bf16_f32 v47, v48, v49
	v_lshlrev_b32_e32 v48, 16, v82
	v_fmac_f32_e32 v42, 0x3fb504f3, v48
	v_and_b32_e32 v48, 0xffff0000, v82
	v_fmac_f32_e32 v43, 0x3fb504f3, v48
	v_cvt_pk_bf16_f32 v48, v42, v43
	v_lshlrev_b32_e32 v42, 16, v83
	v_fmac_f32_e32 v44, 0x3fb504f3, v42
	v_and_b32_e32 v42, 0xffff0000, v83
	v_fmac_f32_e32 v45, 0x3fb504f3, v42
	v_lshlrev_b32_e32 v42, 16, v84
	v_fmac_f32_e32 v38, 0x3fb504f3, v42
	v_and_b32_e32 v42, 0xffff0000, v84
	v_fmac_f32_e32 v39, 0x3fb504f3, v42
	v_cvt_pk_bf16_f32 v49, v44, v45
	global_store_dwordx4 v[102:103], v[46:49], off
	v_cvt_pk_bf16_f32 v38, v38, v39
	v_lshlrev_b32_e32 v39, 16, v85
	v_fmac_f32_e32 v40, 0x3fb504f3, v39
	v_and_b32_e32 v39, 0xffff0000, v85
	v_fmac_f32_e32 v41, 0x3fb504f3, v39
	v_cvt_pk_bf16_f32 v39, v40, v41
	v_lshlrev_b32_e32 v40, 16, v86
	v_fmac_f32_e32 v34, 0x3fb504f3, v40
	v_and_b32_e32 v40, 0xffff0000, v86
	v_fmac_f32_e32 v35, 0x3fb504f3, v40
	v_cvt_pk_bf16_f32 v40, v34, v35
	v_lshlrev_b32_e32 v34, 16, v87
	v_fmac_f32_e32 v36, 0x3fb504f3, v34
	v_and_b32_e32 v34, 0xffff0000, v87
	v_fmac_f32_e32 v37, 0x3fb504f3, v34
	v_lshlrev_b32_e32 v34, 16, v88
	v_fmac_f32_e32 v30, 0x3fb504f3, v34
	v_and_b32_e32 v34, 0xffff0000, v88
	v_fmac_f32_e32 v31, 0x3fb504f3, v34
	v_cvt_pk_bf16_f32 v41, v36, v37
	global_store_dwordx4 v[102:103], v[38:41], off offset:256
	v_cvt_pk_bf16_f32 v30, v30, v31
	v_lshlrev_b32_e32 v31, 16, v89
	v_fmac_f32_e32 v32, 0x3fb504f3, v31
	v_and_b32_e32 v31, 0xffff0000, v89
	v_fmac_f32_e32 v33, 0x3fb504f3, v31
	v_cvt_pk_bf16_f32 v31, v32, v33
	v_lshlrev_b32_e32 v32, 16, v90
	v_fmac_f32_e32 v26, 0x3fb504f3, v32
	v_and_b32_e32 v32, 0xffff0000, v90
	v_fmac_f32_e32 v27, 0x3fb504f3, v32
	v_cvt_pk_bf16_f32 v32, v26, v27
	v_lshlrev_b32_e32 v26, 16, v91
	v_fmac_f32_e32 v28, 0x3fb504f3, v26
	v_and_b32_e32 v26, 0xffff0000, v91
	v_fmac_f32_e32 v29, 0x3fb504f3, v26
	v_lshlrev_b32_e32 v26, 16, v92
	v_fmac_f32_e32 v22, 0x3fb504f3, v26
	v_and_b32_e32 v26, 0xffff0000, v92
	v_fmac_f32_e32 v23, 0x3fb504f3, v26
	v_cvt_pk_bf16_f32 v33, v28, v29
	global_store_dwordx4 v[104:105], v[30:33], off
	v_cvt_pk_bf16_f32 v22, v22, v23
	v_lshlrev_b32_e32 v23, 16, v93
	v_fmac_f32_e32 v24, 0x3fb504f3, v23
	v_and_b32_e32 v23, 0xffff0000, v93
	v_fmac_f32_e32 v25, 0x3fb504f3, v23
	v_cvt_pk_bf16_f32 v23, v24, v25
	v_lshlrev_b32_e32 v24, 16, v94
	v_fmac_f32_e32 v18, 0x3fb504f3, v24
	v_and_b32_e32 v24, 0xffff0000, v94
	v_fmac_f32_e32 v19, 0x3fb504f3, v24
	v_cvt_pk_bf16_f32 v24, v18, v19
	v_lshlrev_b32_e32 v18, 16, v95
	v_fmac_f32_e32 v20, 0x3fb504f3, v18
	v_and_b32_e32 v18, 0xffff0000, v95
	v_fmac_f32_e32 v21, 0x3fb504f3, v18
	v_lshlrev_b32_e32 v18, 16, v96
	v_fmac_f32_e32 v14, 0x3fb504f3, v18
	v_and_b32_e32 v18, 0xffff0000, v96
	v_fmac_f32_e32 v15, 0x3fb504f3, v18
	v_cvt_pk_bf16_f32 v25, v20, v21
	global_store_dwordx4 v[104:105], v[22:25], off offset:256
	v_cvt_pk_bf16_f32 v14, v14, v15
	v_lshlrev_b32_e32 v15, 16, v97
	v_fmac_f32_e32 v16, 0x3fb504f3, v15
	v_and_b32_e32 v15, 0xffff0000, v97
	v_fmac_f32_e32 v17, 0x3fb504f3, v15
	v_cvt_pk_bf16_f32 v15, v16, v17
	v_lshlrev_b32_e32 v16, 16, v98
	v_fmac_f32_e32 v10, 0x3fb504f3, v16
	v_and_b32_e32 v16, 0xffff0000, v98
	v_fmac_f32_e32 v11, 0x3fb504f3, v16
	v_cvt_pk_bf16_f32 v16, v10, v11
	v_lshlrev_b32_e32 v10, 16, v99
	v_fmac_f32_e32 v12, 0x3fb504f3, v10
	v_and_b32_e32 v10, 0xffff0000, v99
	v_fmac_f32_e32 v13, 0x3fb504f3, v10
	v_lshlrev_b32_e32 v10, 16, v66
	v_fmac_f32_e32 v6, 0x3fb504f3, v10
	v_and_b32_e32 v10, 0xffff0000, v66
	v_fmac_f32_e32 v7, 0x3fb504f3, v10
	v_cvt_pk_bf16_f32 v17, v12, v13
	global_store_dwordx4 v[70:71], v[14:17], off
	v_cvt_pk_bf16_f32 v6, v6, v7
	v_lshlrev_b32_e32 v7, 16, v67
	v_fmac_f32_e32 v8, 0x3fb504f3, v7
	v_and_b32_e32 v7, 0xffff0000, v67
	v_fmac_f32_e32 v9, 0x3fb504f3, v7
	v_cvt_pk_bf16_f32 v7, v8, v9
	v_lshlrev_b32_e32 v8, 16, v68
	v_fmac_f32_e32 v2, 0x3fb504f3, v8
	v_and_b32_e32 v8, 0xffff0000, v68
	v_fmac_f32_e32 v3, 0x3fb504f3, v8
	v_cvt_pk_bf16_f32 v8, v2, v3
	v_lshlrev_b32_e32 v2, 16, v69
	v_fmac_f32_e32 v4, 0x3fb504f3, v2
	v_and_b32_e32 v2, 0xffff0000, v69
	v_fmac_f32_e32 v5, 0x3fb504f3, v2
	v_cvt_pk_bf16_f32 v9, v4, v5
	global_store_dwordx4 v[70:71], v[6:9], off offset:256
	s_cbranch_scc1 .LBB0_445
	s_andn2_b64 vcc, exec, s[26:27]
	s_cbranch_vccnz .LBB0_444
	s_branch .LBB0_444
